# GEMM K-loops: closing barrier of each compute segment hoisted above its last 4 MFMAs (tail at prio 2); prompt attention item: waves 4-7 staggered after the staging barrier; plus the sample-tile de-ser
# speedup vs baseline: 1.0069x; 1.0069x over previous
; #define PG8_STAGE(bufoff, gbase, voff) do { _Pragma("unroll") for (int _i = 0; _i < 2; ++_i) \
;         __builtin_amdgcn_global_load_lds((const unsigned*)((const char*)(gbase) + (voff)[_i]), (PG8_LAS unsigned*)(lds + (bufoff) + ldsw + _i * 8192), 16, 0, 0); } while (0)
; #define PG8_LDA(dst, b, h) do { _Pragma("unroll") for (int m = 0; m < 4; ++m) _Pragma("unroll") for (int k = 0; k < 2; ++k) dst[m][k] = *(const PG8_LAS bf16x8*)(lds + PG8_SA(b, h) + aoff + m * 2048 + k * 1024); } while (0)
; #define PG8_LDB(dst, b, h) do { _Pragma("unroll") for (int n = 0; n < 2; ++n) _Pragma("unroll") for (int k = 0; k < 2; ++k) dst[n][k] = *(const PG8_LAS bf16x8*)(lds + PG8_SB(b, h) + boff + n * 2048 + k * 1024); } while (0)
; #define PG8_MMA(ai, bj, At, Bt) do { __builtin_amdgcn_s_setprio(1); _Pragma("unroll") for (int m = 0; m < 4; ++m) _Pragma("unroll") for (int n = 0; n < 2; ++n) _Pragma("unroll") for (int k = 0; k < 2; ++k) \
;         acc[ai][bj][m][n] = __builtin_amdgcn_mfma_f32_16x16x32_bf16(Bt[n][k], At[m][k], acc[ai][bj][m][n], 0, 0, 0); __builtin_amdgcn_s_setprio(0); } while (0)
; #define PG8_WAIT_V(n) asm volatile("s_waitcnt vmcnt(" #n ")" ::: "memory")
; #define PG8_WAIT_L(n) asm volatile("s_waitcnt lgkmcnt(" #n ")" ::: "memory")
; #define PG8_BAR __builtin_amdgcn_s_barrier()
; #define PG8_SCHED __builtin_amdgcn_sched_barrier(0)
; template <class Epi, class Sched, bool ALIGN_EPI = false, bool SP2 = false>
; __device__ __forceinline__ void gemm_phase(PG8_LAS unsigned char* lds, const Gemm g, const Sched& S, const Epi& E) {
;     ...
;             PG8_LDB(B0, 0, 0); PG8_LDB(B1, 0, 1); PG8_SCHED; PG8_LDA(At, 0, 0); PG8_STAGE(PG8_SA(1, 1), a1 + hstep, voffA);
;             PG8_WAIT_V(8); PG8_WAIT_L(0); PG8_BAR; PG8_MMA(0, 0, At, B0); PG8_MMA(0, 1, At, B1); PG8_BAR; PG8_SCHED;
;             PG8_LDA(At, 0, 1); PG8_STAGE(PG8_SB(0, 0), b2, voffB); PG8_STAGE(PG8_SB(0, 1), b2 + hstep, voffB); PG8_STAGE(PG8_SA(0, 0), a2, voffA);
;             PG8_WAIT_V(8); PG8_WAIT_L(0); PG8_BAR; PG8_MMA(1, 0, At, B0); PG8_MMA(1, 1, At, B1); PG8_BAR; PG8_SCHED;
.LBB0_274:
	s_add_u32 s22, s20, 0xfffc0080
	s_addc_u32 s23, s21, -1
	s_add_i32 s39, 0, 0x10000
	s_cmp_eq_u32 s38, 12
	s_cselect_b32 s25, s5, s23
	s_cselect_b32 s24, s13, s22
	v_add_u32_e32 v148, s39, v151
	s_cselect_b32 s23, s11, s37
	s_cselect_b32 s22, s35, s36
	s_add_i32 s45, 0, 0x14000
	ds_read_b128 v[140:143], v148
	ds_read_b128 v[144:147], v148 offset:1024
	ds_read_b128 v[156:159], v148 offset:2048
	ds_read_b128 v[160:163], v148 offset:3072
	v_add_u32_e32 v148, s45, v151
	ds_read_b128 v[164:167], v148
	ds_read_b128 v[168:171], v148 offset:1024
	ds_read_b128 v[182:185], v148 offset:2048
	ds_read_b128 v[186:189], v148 offset:3072
	v_lshl_add_u64 v[148:149], s[20:21], 0, v[136:137]
	s_add_i32 m0, s19, 0xc000
	ds_read_b128 v[190:193], v154
	ds_read_b128 v[194:197], v154 offset:1024
	ds_read_b128 v[198:201], v154 offset:2048
	ds_read_b128 v[202:205], v154 offset:3072
	ds_read_b128 v[228:231], v154 offset:4096
	ds_read_b128 v[236:239], v154 offset:5120
	ds_read_b128 v[240:243], v154 offset:6144
	ds_read_b128 v[244:247], v154 offset:7168
	global_load_lds_dwordx4 v[148:149], off
	v_lshl_add_u64 v[148:149], s[20:21], 0, v[138:139]
	s_add_i32 m0, s19, 0xe000
	s_nop 0
	global_load_lds_dwordx4 v[148:149], off
	s_waitcnt vmcnt(8)
	s_waitcnt lgkmcnt(0)
	s_barrier
	s_setprio 1
	s_waitcnt lgkmcnt(0)
	v_mfma_f32_16x16x32_bf16 v[124:127], v[140:143], v[190:193], v[124:127]
	v_mfma_f32_16x16x32_bf16 v[120:123], v[156:159], v[190:193], v[120:123]
	v_mfma_f32_16x16x32_bf16 v[108:111], v[140:143], v[198:201], v[108:111]
	v_mfma_f32_16x16x32_bf16 v[104:107], v[156:159], v[198:201], v[104:107]
	v_mfma_f32_16x16x32_bf16 v[92:95], v[140:143], v[228:231], v[92:95]
	v_mfma_f32_16x16x32_bf16 v[88:91], v[156:159], v[228:231], v[88:91]
	v_mfma_f32_16x16x32_bf16 v[76:79], v[140:143], v[240:243], v[76:79]
	v_mfma_f32_16x16x32_bf16 v[72:75], v[156:159], v[240:243], v[72:75]
	v_mfma_f32_16x16x32_bf16 v[124:127], v[144:147], v[194:197], v[124:127]
	v_mfma_f32_16x16x32_bf16 v[120:123], v[160:163], v[194:197], v[120:123]
	v_mfma_f32_16x16x32_bf16 v[108:111], v[144:147], v[202:205], v[108:111]
	v_mfma_f32_16x16x32_bf16 v[104:107], v[160:163], v[202:205], v[104:107]
	v_mfma_f32_16x16x32_bf16 v[92:95], v[144:147], v[236:239], v[92:95]
	v_mfma_f32_16x16x32_bf16 v[88:91], v[160:163], v[236:239], v[88:91]
	v_mfma_f32_16x16x32_bf16 v[76:79], v[144:147], v[244:247], v[76:79]
	v_mfma_f32_16x16x32_bf16 v[72:75], v[160:163], v[244:247], v[72:75]
	s_setprio 0
	s_setprio 1
	v_mfma_f32_16x16x32_bf16 v[116:119], v[164:167], v[190:193], v[116:119]
	v_mfma_f32_16x16x32_bf16 v[112:115], v[182:185], v[190:193], v[112:115]
	v_mfma_f32_16x16x32_bf16 v[100:103], v[164:167], v[198:201], v[100:103]
	v_mfma_f32_16x16x32_bf16 v[96:99], v[182:185], v[198:201], v[96:99]
	v_mfma_f32_16x16x32_bf16 v[84:87], v[164:167], v[228:231], v[84:87]
	v_mfma_f32_16x16x32_bf16 v[80:83], v[182:185], v[228:231], v[80:83]
	v_mfma_f32_16x16x32_bf16 v[68:71], v[164:167], v[240:243], v[68:71]
	v_mfma_f32_16x16x32_bf16 v[64:67], v[182:185], v[240:243], v[64:67]
	v_mfma_f32_16x16x32_bf16 v[116:119], v[168:171], v[194:197], v[116:119]
	v_mfma_f32_16x16x32_bf16 v[112:115], v[186:189], v[194:197], v[112:115]
	v_mfma_f32_16x16x32_bf16 v[100:103], v[168:171], v[202:205], v[100:103]
	v_mfma_f32_16x16x32_bf16 v[96:99], v[186:189], v[202:205], v[96:99]
	s_setprio 2
	s_barrier
	v_mfma_f32_16x16x32_bf16 v[84:87], v[168:171], v[236:239], v[84:87]
	v_mfma_f32_16x16x32_bf16 v[80:83], v[186:189], v[236:239], v[80:83]
	v_mfma_f32_16x16x32_bf16 v[68:71], v[168:171], v[244:247], v[68:71]
	v_mfma_f32_16x16x32_bf16 v[64:67], v[186:189], v[244:247], v[64:67]
	s_setprio 0
	s_add_i32 s39, s39, s26
	v_lshl_add_u64 v[148:149], s[22:23], 0, v[130:131]
	s_mov_b32 m0, s39
	ds_read_b128 v[190:193], v154 offset:16384
	ds_read_b128 v[194:197], v154 offset:17408
	ds_read_b128 v[198:201], v154 offset:18432
	ds_read_b128 v[202:205], v154 offset:19456
	ds_read_b128 v[228:231], v154 offset:20480
	ds_read_b128 v[236:239], v154 offset:21504
	ds_read_b128 v[240:243], v154 offset:22528
	ds_read_b128 v[244:247], v154 offset:23552
	global_load_lds_dwordx4 v[148:149], off
	s_add_i32 m0, s39, 0x2000
	s_add_u32 s52, s22, 0x40000
	v_lshl_add_u64 v[206:207], s[22:23], 0, v[134:135]
	s_addc_u32 s53, s23, 0
	s_add_i32 s39, s45, s26
	global_load_lds_dwordx4 v[206:207], off
	v_lshl_add_u64 v[248:249], s[52:53], 0, v[130:131]
	s_mov_b32 m0, s39
	v_lshl_add_u64 v[250:251], s[24:25], 0, v[132:133]
	global_load_lds_dwordx4 v[248:249], off
	v_lshl_add_u64 v[248:249], s[52:53], 0, v[134:135]
	s_add_i32 m0, s39, 0x2000
	s_nop 0
	global_load_lds_dwordx4 v[248:249], off
	v_lshl_add_u64 v[248:249], s[24:25], 0, v[128:129]
	s_mov_b32 m0, s19
	s_nop 0
	global_load_lds_dwordx4 v[248:249], off
	s_mov_b32 m0, s27
	s_nop 0
	global_load_lds_dwordx4 v[250:251], off
	s_waitcnt vmcnt(8)
	s_waitcnt lgkmcnt(0)
	s_barrier
; #define PG8_STAGE(bufoff, gbase, voff) do { _Pragma("unroll") for (int _i = 0; _i < 2; ++_i) \
;         __builtin_amdgcn_global_load_lds((const unsigned*)((const char*)(gbase) + (voff)[_i]), (PG8_LAS unsigned*)(lds + (bufoff) + ldsw + _i * 8192), 16, 0, 0); } while (0)
; #define PG8_LDA(dst, b, h) do { _Pragma("unroll") for (int m = 0; m < 4; ++m) _Pragma("unroll") for (int k = 0; k < 2; ++k) dst[m][k] = *(const PG8_LAS bf16x8*)(lds + PG8_SA(b, h) + aoff + m * 2048 + k * 1024); } while (0)
; #define PG8_LDB(dst, b, h) do { _Pragma("unroll") for (int n = 0; n < 2; ++n) _Pragma("unroll") for (int k = 0; k < 2; ++k) dst[n][k] = *(const PG8_LAS bf16x8*)(lds + PG8_SB(b, h) + boff + n * 2048 + k * 1024); } while (0)
; #define PG8_MMA(ai, bj, At, Bt) do { __builtin_amdgcn_s_setprio(1); _Pragma("unroll") for (int m = 0; m < 4; ++m) _Pragma("unroll") for (int n = 0; n < 2; ++n) _Pragma("unroll") for (int k = 0; k < 2; ++k) \
;         acc[ai][bj][m][n] = __builtin_amdgcn_mfma_f32_16x16x32_bf16(Bt[n][k], At[m][k], acc[ai][bj][m][n], 0, 0, 0); __builtin_amdgcn_s_setprio(0); } while (0)
; #define PG8_WAIT_V(n) asm volatile("s_waitcnt vmcnt(" #n ")" ::: "memory")
; #define PG8_WAIT_L(n) asm volatile("s_waitcnt lgkmcnt(" #n ")" ::: "memory")
; #define PG8_BAR __builtin_amdgcn_s_barrier()
; #define PG8_SCHED __builtin_amdgcn_sched_barrier(0)
; template <class Epi, class Sched, bool ALIGN_EPI = false, bool SP2 = false>
; __device__ __forceinline__ void gemm_phase(PG8_LAS unsigned char* lds, const Gemm g, const Sched& S, const Epi& E) {
;     ...
;             PG8_WAIT_V(8); PG8_WAIT_L(0); PG8_BAR; PG8_MMA(1, 0, At, B0); PG8_MMA(1, 1, At, B1); PG8_BAR; PG8_SCHED;
;             PG8_LDB(B0, 1, 0); PG8_LDB(B1, 1, 1); PG8_SCHED; PG8_LDA(At, 1, 0); PG8_STAGE(PG8_SA(0, 1), a2 + hstep, voffA);
;             PG8_WAIT_V(8); PG8_WAIT_L(0); PG8_BAR; PG8_MMA(0, 0, At, B0); PG8_MMA(0, 1, At, B1); PG8_BAR; PG8_SCHED;
	s_setprio 1
	s_waitcnt lgkmcnt(0)
	v_mfma_f32_16x16x32_bf16 v[60:63], v[140:143], v[190:193], v[60:63]
	v_mfma_f32_16x16x32_bf16 v[56:59], v[156:159], v[190:193], v[56:59]
	v_mfma_f32_16x16x32_bf16 v[44:47], v[140:143], v[198:201], v[44:47]
	v_mfma_f32_16x16x32_bf16 v[40:43], v[156:159], v[198:201], v[40:43]
	v_mfma_f32_16x16x32_bf16 v[28:31], v[140:143], v[228:231], v[28:31]
	v_mfma_f32_16x16x32_bf16 v[24:27], v[156:159], v[228:231], v[24:27]
	v_mfma_f32_16x16x32_bf16 v[12:15], v[140:143], v[240:243], v[12:15]
	v_mfma_f32_16x16x32_bf16 v[8:11], v[156:159], v[240:243], v[8:11]
	v_mfma_f32_16x16x32_bf16 v[60:63], v[144:147], v[194:197], v[60:63]
	v_mfma_f32_16x16x32_bf16 v[56:59], v[160:163], v[194:197], v[56:59]
	v_mfma_f32_16x16x32_bf16 v[44:47], v[144:147], v[202:205], v[44:47]
	v_mfma_f32_16x16x32_bf16 v[40:43], v[160:163], v[202:205], v[40:43]
	v_mfma_f32_16x16x32_bf16 v[28:31], v[144:147], v[236:239], v[28:31]
	v_mfma_f32_16x16x32_bf16 v[24:27], v[160:163], v[236:239], v[24:27]
	v_mfma_f32_16x16x32_bf16 v[12:15], v[144:147], v[244:247], v[12:15]
	v_mfma_f32_16x16x32_bf16 v[8:11], v[160:163], v[244:247], v[8:11]
	s_setprio 0
	s_setprio 1
	v_mfma_f32_16x16x32_bf16 v[52:55], v[164:167], v[190:193], v[52:55]
	v_mfma_f32_16x16x32_bf16 v[48:51], v[182:185], v[190:193], v[48:51]
	v_mfma_f32_16x16x32_bf16 v[36:39], v[164:167], v[198:201], v[36:39]
	v_mfma_f32_16x16x32_bf16 v[32:35], v[182:185], v[198:201], v[32:35]
	v_mfma_f32_16x16x32_bf16 v[20:23], v[164:167], v[228:231], v[20:23]
	v_mfma_f32_16x16x32_bf16 v[16:19], v[182:185], v[228:231], v[16:19]
	v_mfma_f32_16x16x32_bf16 v[4:7], v[164:167], v[240:243], v[4:7]
	v_mfma_f32_16x16x32_bf16 v[0:3], v[182:185], v[240:243], v[0:3]
	v_mfma_f32_16x16x32_bf16 v[52:55], v[168:171], v[194:197], v[52:55]
	v_mfma_f32_16x16x32_bf16 v[48:51], v[186:189], v[194:197], v[48:51]
	v_mfma_f32_16x16x32_bf16 v[36:39], v[168:171], v[202:205], v[36:39]
	v_mfma_f32_16x16x32_bf16 v[32:35], v[186:189], v[202:205], v[32:35]
	s_setprio 2
	s_barrier
	v_mfma_f32_16x16x32_bf16 v[20:23], v[168:171], v[236:239], v[20:23]
	v_mfma_f32_16x16x32_bf16 v[16:19], v[186:189], v[236:239], v[16:19]
	v_mfma_f32_16x16x32_bf16 v[4:7], v[168:171], v[244:247], v[4:7]
	v_mfma_f32_16x16x32_bf16 v[0:3], v[186:189], v[244:247], v[0:3]
	s_setprio 0
	s_add_i32 s39, 0, 0x18000
	v_add_u32_e32 v155, s39, v151
	s_add_i32 s45, 0, 0x1c000
	ds_read_b128 v[140:143], v155
	ds_read_b128 v[144:147], v155 offset:1024
	ds_read_b128 v[156:159], v155 offset:2048
	ds_read_b128 v[160:163], v155 offset:3072
	v_add_u32_e32 v155, s45, v151
	ds_read_b128 v[164:167], v155
	ds_read_b128 v[168:171], v155 offset:1024
	ds_read_b128 v[182:185], v155 offset:2048
	ds_read_b128 v[186:189], v155 offset:3072
	s_add_u32 s24, s24, 0x40000
	s_addc_u32 s25, s25, 0
	s_mov_b32 m0, s28
	v_lshl_add_u64 v[210:211], s[24:25], 0, v[128:129]
	ds_read_b128 v[190:193], v154 offset:32768
	ds_read_b128 v[194:197], v154 offset:33792
	ds_read_b128 v[198:201], v154 offset:34816
	ds_read_b128 v[202:205], v154 offset:35840
	ds_read_b128 v[228:231], v154 offset:36864
	ds_read_b128 v[236:239], v154 offset:37888
	ds_read_b128 v[240:243], v154 offset:38912
	ds_read_b128 v[244:247], v154 offset:39936
	global_load_lds_dwordx4 v[210:211], off
	v_lshl_add_u64 v[210:211], s[24:25], 0, v[132:133]
	s_mov_b32 m0, s29
	s_nop 0
	global_load_lds_dwordx4 v[210:211], off
	s_waitcnt vmcnt(8)
	s_waitcnt lgkmcnt(0)
	s_barrier
	s_setprio 1
	s_waitcnt lgkmcnt(0)
	v_mfma_f32_16x16x32_bf16 v[124:127], v[140:143], v[190:193], v[124:127]
	v_mfma_f32_16x16x32_bf16 v[120:123], v[156:159], v[190:193], v[120:123]
	v_mfma_f32_16x16x32_bf16 v[108:111], v[140:143], v[198:201], v[108:111]
	v_mfma_f32_16x16x32_bf16 v[104:107], v[156:159], v[198:201], v[104:107]
	v_mfma_f32_16x16x32_bf16 v[92:95], v[140:143], v[228:231], v[92:95]
	v_mfma_f32_16x16x32_bf16 v[88:91], v[156:159], v[228:231], v[88:91]
	v_mfma_f32_16x16x32_bf16 v[76:79], v[140:143], v[240:243], v[76:79]
	v_mfma_f32_16x16x32_bf16 v[72:75], v[156:159], v[240:243], v[72:75]
	v_mfma_f32_16x16x32_bf16 v[124:127], v[144:147], v[194:197], v[124:127]
	v_mfma_f32_16x16x32_bf16 v[120:123], v[160:163], v[194:197], v[120:123]
	v_mfma_f32_16x16x32_bf16 v[108:111], v[144:147], v[202:205], v[108:111]
	v_mfma_f32_16x16x32_bf16 v[104:107], v[160:163], v[202:205], v[104:107]
	v_mfma_f32_16x16x32_bf16 v[92:95], v[144:147], v[236:239], v[92:95]
	v_mfma_f32_16x16x32_bf16 v[88:91], v[160:163], v[236:239], v[88:91]
	v_mfma_f32_16x16x32_bf16 v[76:79], v[144:147], v[244:247], v[76:79]
	v_mfma_f32_16x16x32_bf16 v[72:75], v[160:163], v[244:247], v[72:75]
	s_setprio 0
	s_setprio 1
	v_mfma_f32_16x16x32_bf16 v[116:119], v[164:167], v[190:193], v[116:119]
	v_mfma_f32_16x16x32_bf16 v[112:115], v[182:185], v[190:193], v[112:115]
	v_mfma_f32_16x16x32_bf16 v[100:103], v[164:167], v[198:201], v[100:103]
	v_mfma_f32_16x16x32_bf16 v[96:99], v[182:185], v[198:201], v[96:99]
	v_mfma_f32_16x16x32_bf16 v[84:87], v[164:167], v[228:231], v[84:87]
	v_mfma_f32_16x16x32_bf16 v[80:83], v[182:185], v[228:231], v[80:83]
	v_mfma_f32_16x16x32_bf16 v[68:71], v[164:167], v[240:243], v[68:71]
	v_mfma_f32_16x16x32_bf16 v[64:67], v[182:185], v[240:243], v[64:67]
	v_mfma_f32_16x16x32_bf16 v[116:119], v[168:171], v[194:197], v[116:119]
	v_mfma_f32_16x16x32_bf16 v[112:115], v[186:189], v[194:197], v[112:115]
	v_mfma_f32_16x16x32_bf16 v[100:103], v[168:171], v[202:205], v[100:103]
	v_mfma_f32_16x16x32_bf16 v[96:99], v[186:189], v[202:205], v[96:99]
	s_setprio 2
	s_barrier
; #define PG8_STAGE(bufoff, gbase, voff) do { _Pragma("unroll") for (int _i = 0; _i < 2; ++_i) \
;         __builtin_amdgcn_global_load_lds((const unsigned*)((const char*)(gbase) + (voff)[_i]), (PG8_LAS unsigned*)(lds + (bufoff) + ldsw + _i * 8192), 16, 0, 0); } while (0)
; #define PG8_LDA(dst, b, h) do { _Pragma("unroll") for (int m = 0; m < 4; ++m) _Pragma("unroll") for (int k = 0; k < 2; ++k) dst[m][k] = *(const PG8_LAS bf16x8*)(lds + PG8_SA(b, h) + aoff + m * 2048 + k * 1024); } while (0)
; #define PG8_MMA(ai, bj, At, Bt) do { __builtin_amdgcn_s_setprio(1); _Pragma("unroll") for (int m = 0; m < 4; ++m) _Pragma("unroll") for (int n = 0; n < 2; ++n) _Pragma("unroll") for (int k = 0; k < 2; ++k) \
;         acc[ai][bj][m][n] = __builtin_amdgcn_mfma_f32_16x16x32_bf16(Bt[n][k], At[m][k], acc[ai][bj][m][n], 0, 0, 0); __builtin_amdgcn_s_setprio(0); } while (0)
; #define PG8_WAIT_V(n) asm volatile("s_waitcnt vmcnt(" #n ")" ::: "memory")
; #define PG8_WAIT_L(n) asm volatile("s_waitcnt lgkmcnt(" #n ")" ::: "memory")
; #define PG8_BAR __builtin_amdgcn_s_barrier()
; #define PG8_SCHED __builtin_amdgcn_sched_barrier(0)
; template <class Epi, class Sched, bool ALIGN_EPI = false, bool SP2 = false>
; __device__ __forceinline__ void gemm_phase(PG8_LAS unsigned char* lds, const Gemm g, const Sched& S, const Epi& E) {
;     ...
;         for (int t = 0; t < nt; t += 2) {
;     ...
;             PG8_WAIT_V(8); PG8_WAIT_L(0); PG8_BAR; PG8_MMA(0, 0, At, B0); PG8_MMA(0, 1, At, B1); PG8_BAR; PG8_SCHED;
;             PG8_LDA(At, 1, 1); PG8_STAGE(PG8_SB(1, 0), b3, voffB); PG8_STAGE(PG8_SB(1, 1), b3 + hstep, voffB); PG8_STAGE(PG8_SA(1, 0), a3, voffA);
;             PG8_WAIT_V(8); PG8_WAIT_L(0); PG8_BAR; PG8_MMA(1, 0, At, B0); PG8_MMA(1, 1, At, B1); PG8_BAR; PG8_SCHED;
	v_mfma_f32_16x16x32_bf16 v[84:87], v[168:171], v[236:239], v[84:87]
	v_mfma_f32_16x16x32_bf16 v[80:83], v[186:189], v[236:239], v[80:83]
	v_mfma_f32_16x16x32_bf16 v[68:71], v[168:171], v[244:247], v[68:71]
	v_mfma_f32_16x16x32_bf16 v[64:67], v[186:189], v[244:247], v[64:67]
	s_setprio 0
	s_add_i32 s24, s39, s26
	v_lshl_add_u64 v[148:149], v[148:149], 0, s[88:89]
	s_mov_b32 m0, s24
	ds_read_b128 v[190:193], v154 offset:49152
	ds_read_b128 v[194:197], v154 offset:50176
	ds_read_b128 v[198:201], v154 offset:51200
	ds_read_b128 v[202:205], v154 offset:52224
	ds_read_b128 v[228:231], v154 offset:53248
	ds_read_b128 v[236:239], v154 offset:54272
	ds_read_b128 v[240:243], v154 offset:55296
	ds_read_b128 v[244:247], v154 offset:56320
	global_load_lds_dwordx4 v[148:149], off
	s_add_i32 m0, s24, 0x2000
	s_add_u32 s22, s22, 0x40080
	v_lshl_add_u64 v[148:149], v[206:207], 0, s[88:89]
	s_addc_u32 s23, s23, 0
	s_add_i32 s24, s45, s26
	global_load_lds_dwordx4 v[148:149], off
	v_lshl_add_u64 v[148:149], s[22:23], 0, v[130:131]
	s_mov_b32 m0, s24
	s_nop 0
	global_load_lds_dwordx4 v[148:149], off
	v_lshl_add_u64 v[148:149], s[22:23], 0, v[134:135]
	s_add_i32 m0, s24, 0x2000
	s_nop 0
	global_load_lds_dwordx4 v[148:149], off
	v_lshl_add_u64 v[148:149], v[248:249], 0, s[88:89]
	s_mov_b32 m0, s30
	s_nop 0
	global_load_lds_dwordx4 v[148:149], off
	v_lshl_add_u64 v[148:149], v[250:251], 0, s[88:89]
	s_mov_b32 m0, s31
	s_nop 0
	global_load_lds_dwordx4 v[148:149], off
	s_waitcnt vmcnt(8)
	s_waitcnt lgkmcnt(0)
	s_barrier
	s_setprio 1
	s_waitcnt lgkmcnt(0)
	v_mfma_f32_16x16x32_bf16 v[60:63], v[140:143], v[190:193], v[60:63]
	v_mfma_f32_16x16x32_bf16 v[56:59], v[156:159], v[190:193], v[56:59]
	v_mfma_f32_16x16x32_bf16 v[44:47], v[140:143], v[198:201], v[44:47]
	v_mfma_f32_16x16x32_bf16 v[40:43], v[156:159], v[198:201], v[40:43]
	v_mfma_f32_16x16x32_bf16 v[28:31], v[140:143], v[228:231], v[28:31]
	v_mfma_f32_16x16x32_bf16 v[24:27], v[156:159], v[228:231], v[24:27]
	v_mfma_f32_16x16x32_bf16 v[12:15], v[140:143], v[240:243], v[12:15]
	v_mfma_f32_16x16x32_bf16 v[8:11], v[156:159], v[240:243], v[8:11]
	v_mfma_f32_16x16x32_bf16 v[60:63], v[144:147], v[194:197], v[60:63]
	v_mfma_f32_16x16x32_bf16 v[56:59], v[160:163], v[194:197], v[56:59]
	v_mfma_f32_16x16x32_bf16 v[44:47], v[144:147], v[202:205], v[44:47]
	v_mfma_f32_16x16x32_bf16 v[40:43], v[160:163], v[202:205], v[40:43]
	v_mfma_f32_16x16x32_bf16 v[28:31], v[144:147], v[236:239], v[28:31]
	v_mfma_f32_16x16x32_bf16 v[24:27], v[160:163], v[236:239], v[24:27]
	v_mfma_f32_16x16x32_bf16 v[12:15], v[144:147], v[244:247], v[12:15]
	v_mfma_f32_16x16x32_bf16 v[8:11], v[160:163], v[244:247], v[8:11]
	s_setprio 0
	s_setprio 1
	v_mfma_f32_16x16x32_bf16 v[52:55], v[164:167], v[190:193], v[52:55]
	v_mfma_f32_16x16x32_bf16 v[48:51], v[182:185], v[190:193], v[48:51]
	v_mfma_f32_16x16x32_bf16 v[36:39], v[164:167], v[198:201], v[36:39]
	v_mfma_f32_16x16x32_bf16 v[32:35], v[182:185], v[198:201], v[32:35]
	v_mfma_f32_16x16x32_bf16 v[20:23], v[164:167], v[228:231], v[20:23]
	v_mfma_f32_16x16x32_bf16 v[16:19], v[182:185], v[228:231], v[16:19]
	v_mfma_f32_16x16x32_bf16 v[4:7], v[164:167], v[240:243], v[4:7]
	v_mfma_f32_16x16x32_bf16 v[0:3], v[182:185], v[240:243], v[0:3]
	v_mfma_f32_16x16x32_bf16 v[52:55], v[168:171], v[194:197], v[52:55]
	v_mfma_f32_16x16x32_bf16 v[48:51], v[186:189], v[194:197], v[48:51]
	v_mfma_f32_16x16x32_bf16 v[36:39], v[168:171], v[202:205], v[36:39]
	v_mfma_f32_16x16x32_bf16 v[32:35], v[186:189], v[202:205], v[32:35]
	s_setprio 2
	s_barrier
	v_mfma_f32_16x16x32_bf16 v[20:23], v[168:171], v[236:239], v[20:23]
	v_mfma_f32_16x16x32_bf16 v[16:19], v[186:189], v[236:239], v[16:19]
	v_mfma_f32_16x16x32_bf16 v[4:7], v[168:171], v[244:247], v[4:7]
	v_mfma_f32_16x16x32_bf16 v[0:3], v[186:189], v[244:247], v[0:3]
	s_setprio 0
	s_add_i32 s38, s38, 2
	s_add_u32 s20, s20, 0x100
	s_addc_u32 s21, s21, 0
	s_add_u32 s36, s36, 0x100
	s_addc_u32 s37, s37, 0
	s_cmp_gt_u32 s38, 13
	s_cbranch_scc0 .LBB0_274
	s_and_b64 vcc, exec, s[8:9]
	s_cbranch_vccz .LBB0_295
	s_barrier
	v_lshl_add_u32 v155, s4, 8, v150
	s_cmp_gt_i32 s18, 7
	s_mov_b64 s[4:5], -1
	s_cbranch_scc1 .LBB0_296

; template <bool SAMPLE> ...
;     const int r32 = lane & 31, hi = lane >> 5;
;     const int myhead = SAMPLE ? head0 + (r32 >> 3) : head0;
;     const int mypos = SAMPLE ? pos0 + (r32 & 7) : pos0 + r32;
;     float q[4][8];
; #pragma unroll
;     for (int d0 = 0; d0 < 4; ++d0) unpack8(qw[d0], q[d0]);
;     float ss = 0.f;
; #pragma unroll
;     for (int d0 = 0; d0 < 4; ++d0)
; #pragma unroll
;         for (int i = 0; i < 8; ++i) ss += q[d0][i] * q[d0][i];
;     ss += __shfl_xor(ss, 32);
;     const float rstd = rsqrtf(ss * (1.0f / 64.0f) + EPS);
; #pragma unroll
;     for (int d0 = 0; d0 < 4; ++d0) { const f32x4 g0 = *(const f32x4*)(qg + d0 * 16 + hi * 8), g1 = *(const f32x4*)(qg + d0 * 16 + hi * 8 + 4);
;         q[d0][0] *= rstd * g0.x; q[d0][1] *= rstd * g0.y; q[d0][2] *= rstd * g0.z; q[d0][3] *= rstd * g0.w; q[d0][4] *= rstd * g1.x; q[d0][5] *= rstd * g1.y; q[d0][6] *= rstd * g1.z; q[d0][7] *= rstd * g1.w; }
;     {
;         const float* tr = tab + (size_t)mypos * 16;
;         const f32x4 c0 = *(const f32x4*)(tr), c1 = *(const f32x4*)(tr + 4), s0 = *(const f32x4*)(tr + 8), s1 = *(const f32x4*)(tr + 12);
;         const float cs[8] = {c0.x, c0.y, c0.z, c0.w, c1.x, c1.y, c1.z, c1.w}, sn[8] = {s0.x, s0.y, s0.z, s0.w, s1.x, s1.y, s1.z, s1.w};
;         const float sg = (hi == 0) ? -1.0f : 1.0f;
; #pragma unroll
;         for (int i = 0; i < 8; ++i) { const float pr = __shfl_xor(q[0][i], 32); q[0][i] = q[0][i] * cs[i] + sg * pr * sn[i]; }
;     }
; __device__ __forceinline__ void attn_prompt_item(const Args& a, int l, int item, LAS unsigned char* lds, int tid, int lane, int wave) {
;     ...
;     attn_tile32<false>(qw0, zw0, Y, tab, qg, sinks, Kl + 32 * qt0 * 144, Vl + 32 * qt0 * 64, 16384, wsf, ost, rowq0, headw, b * 128 + qt0 * 32, (b == 0) ? 4 - qt0 : 0, lane);
.LBB0_475:
	s_or_b64 exec, exec, s[0:1]
	v_cmp_lt_i32_e32 vcc, v220, v214
	v_and_b32_e32 v172, 32, v132
	s_waitcnt lgkmcnt(0)
	v_cndmask_b32_e32 v16, v213, v220, vcc
	s_barrier
	v_lshlrev_b32_e32 v127, 2, v16
	global_load_dwordx4 v[16:19], v172, s[62:63]
	global_load_dwordx4 v[20:23], v172, s[62:63] offset:16
	global_load_dwordx4 v[24:27], v172, s[62:63] offset:64
	global_load_dwordx4 v[28:31], v172, s[62:63] offset:80
	global_load_dwordx4 v[32:35], v172, s[62:63] offset:128
	global_load_dwordx4 v[36:39], v172, s[62:63] offset:144
	global_load_dwordx4 v[40:43], v172, s[62:63] offset:192
	global_load_dwordx4 v[44:47], v172, s[62:63] offset:208
	v_readfirstlane_b32 s0, v208
	s_nop 3
	s_cmpk_lt_u32 s0, 0x100
	s_cbranch_scc1 .Lstg_skip
	s_sleep 12
.Lstg_skip:
	s_or_b32 s86, s12, s33
	v_or_b32_e32 v48, s86, v134
	v_lshlrev_b32_e32 v60, 6, v48
	global_load_dwordx4 v[48:51], v60, s[48:49] offset:32
	global_load_dwordx4 v[52:55], v60, s[48:49] offset:48
	global_load_dwordx4 v[56:59], v60, s[48:49]
	s_nop 0
	global_load_dwordx4 v[60:63], v60, s[48:49] offset:16
	v_lshlrev_b32_e32 v170, 16, v0
	v_and_b32_e32 v171, 0xffff0000, v0
	v_lshlrev_b32_e32 v166, 16, v1
	v_and_b32_e32 v167, 0xffff0000, v1
	v_pk_mul_f32 v[0:1], v[170:171], v[170:171]
	v_pk_mul_f32 v[168:169], v[166:167], v[166:167]
	v_add_f32_e32 v0, v0, v1
	v_lshlrev_b32_e32 v164, 16, v2
	v_and_b32_e32 v165, 0xffff0000, v2
	v_add_f32_e32 v0, v168, v0
	v_lshlrev_b32_e32 v160, 16, v3
	v_and_b32_e32 v161, 0xffff0000, v3
	v_pk_mul_f32 v[2:3], v[164:165], v[164:165]
	v_add_f32_e32 v0, v169, v0
	v_add_f32_e32 v0, v2, v0
	v_pk_mul_f32 v[162:163], v[160:161], v[160:161]
	v_add_f32_e32 v0, v3, v0
	v_lshlrev_b32_e32 v158, 16, v4
	v_and_b32_e32 v159, 0xffff0000, v4
	v_add_f32_e32 v0, v162, v0
	v_lshlrev_b32_e32 v154, 16, v5
	v_and_b32_e32 v155, 0xffff0000, v5
	v_pk_mul_f32 v[4:5], v[158:159], v[158:159]
	v_add_f32_e32 v0, v163, v0
	v_add_f32_e32 v0, v4, v0
	v_pk_mul_f32 v[156:157], v[154:155], v[154:155]
	v_add_f32_e32 v0, v5, v0
	v_lshlrev_b32_e32 v152, 16, v6
	v_and_b32_e32 v153, 0xffff0000, v6
	v_add_f32_e32 v0, v156, v0
	v_lshlrev_b32_e32 v148, 16, v7
	v_and_b32_e32 v149, 0xffff0000, v7
	v_pk_mul_f32 v[6:7], v[152:153], v[152:153]
	v_add_f32_e32 v0, v157, v0
	v_add_f32_e32 v0, v6, v0
	v_pk_mul_f32 v[150:151], v[148:149], v[148:149]
	v_add_f32_e32 v0, v7, v0
	v_lshlrev_b32_e32 v146, 16, v8
	v_and_b32_e32 v147, 0xffff0000, v8
	v_add_f32_e32 v0, v150, v0
	v_lshlrev_b32_e32 v142, 16, v9
	v_and_b32_e32 v143, 0xffff0000, v9
	v_pk_mul_f32 v[8:9], v[146:147], v[146:147]
	v_add_f32_e32 v0, v151, v0
	v_add_f32_e32 v0, v8, v0
	v_pk_mul_f32 v[144:145], v[142:143], v[142:143]
	v_add_f32_e32 v0, v9, v0
	v_lshlrev_b32_e32 v140, 16, v10
	v_and_b32_e32 v141, 0xffff0000, v10
	v_add_f32_e32 v0, v144, v0
	v_lshlrev_b32_e32 v136, 16, v11
	v_and_b32_e32 v137, 0xffff0000, v11
	v_pk_mul_f32 v[10:11], v[140:141], v[140:141]
	v_add_f32_e32 v0, v145, v0
	v_add_f32_e32 v0, v10, v0
	v_pk_mul_f32 v[138:139], v[136:137], v[136:137]
	v_add_f32_e32 v0, v11, v0
	v_lshlrev_b32_e32 v122, 16, v12
	v_and_b32_e32 v123, 0xffff0000, v12
	v_add_f32_e32 v0, v138, v0
	v_lshlrev_b32_e32 v118, 16, v13
	v_and_b32_e32 v119, 0xffff0000, v13
	v_pk_mul_f32 v[12:13], v[122:123], v[122:123]
	v_add_f32_e32 v0, v139, v0
	v_add_f32_e32 v0, v12, v0
	v_pk_mul_f32 v[120:121], v[118:119], v[118:119]
	v_add_f32_e32 v0, v13, v0
	v_lshlrev_b32_e32 v116, 16, v14
	v_and_b32_e32 v117, 0xffff0000, v14
	v_add_f32_e32 v0, v120, v0
	v_lshlrev_b32_e32 v112, 16, v15
	v_and_b32_e32 v113, 0xffff0000, v15
	v_pk_mul_f32 v[14:15], v[116:117], v[116:117]
	v_add_f32_e32 v0, v121, v0
	v_add_f32_e32 v0, v14, v0
	v_pk_mul_f32 v[114:115], v[112:113], v[112:113]
	v_add_f32_e32 v0, v15, v0
	v_add_f32_e32 v0, v114, v0
	v_add_f32_e32 v0, v115, v0
	ds_bpermute_b32 v1, v127, v0
	v_cmp_gt_u32_e64 s[0:1], 32, v132
	s_cmp_eq_u32 s7, 0
	v_lshrrev_b32_e32 v125, 5, v132
	s_cselect_b64 s[54:55], -1, 0
	s_waitcnt lgkmcnt(0)
	v_add_f32_e32 v0, v0, v1
	v_fmamk_f32 v0, v0, 0x3c800000, v209
	v_mul_f32_e32 v1, 0x4b800000, v0
	v_cmp_gt_f32_e32 vcc, s96, v0
	s_cmp_lg_u32 s7, 0
	s_cselect_b64 s[4:5], -1, 0
	v_cndmask_b32_e32 v0, v0, v1, vcc
	v_rsq_f32_e32 v0, v0
	v_mov_b32_e32 v138, 0xf149f2ca
	v_mov_b32_e32 v139, 0xf149f2ca
	v_mov_b32_e32 v144, 0xf149f2ca
	v_mul_f32_e32 v1, 0x45800000, v0
	v_cndmask_b32_e32 v0, v0, v1, vcc
	s_waitcnt vmcnt(11)
	v_pk_mul_f32 v[2:3], v[16:17], v[0:1] op_sel_hi:[1,0]
	v_pk_mul_f32 v[4:5], v[18:19], v[0:1] op_sel_hi:[1,0]
	v_pk_mul_f32 v[2:3], v[2:3], v[170:171]
	s_waitcnt vmcnt(10)
	v_pk_mul_f32 v[6:7], v[20:21], v[0:1] op_sel_hi:[1,0]
	s_waitcnt vmcnt(7)
	v_pk_mul_f32 v[18:19], v[32:33], v[0:1] op_sel_hi:[1,0]
	v_pk_mul_f32 v[20:21], v[34:35], v[0:1] op_sel_hi:[1,0]
	ds_bpermute_b32 v32, v127, v3
	ds_bpermute_b32 v34, v127, v2
	v_pk_mul_f32 v[4:5], v[4:5], v[166:167]
	ds_bpermute_b32 v35, v127, v5
	v_pk_mul_f32 v[6:7], v[6:7], v[164:165]
	s_waitcnt lgkmcnt(2)
	v_cndmask_b32_e64 v33, v32, -v32, s[0:1]
	s_waitcnt lgkmcnt(1)
	v_cndmask_b32_e64 v32, v34, -v34, s[0:1]
	ds_bpermute_b32 v34, v127, v4
	s_waitcnt vmcnt(3)
	v_pk_mul_f32 v[32:33], v[48:49], v[32:33]
	v_pk_mul_f32 v[8:9], v[22:23], v[0:1] op_sel_hi:[1,0]
	s_waitcnt vmcnt(1)
	v_pk_fma_f32 v[2:3], v[56:57], v[2:3], v[32:33]
	s_waitcnt lgkmcnt(1)
	v_cndmask_b32_e64 v33, v35, -v35, s[0:1]
	ds_bpermute_b32 v35, v127, v7
	s_waitcnt lgkmcnt(1)
	v_cndmask_b32_e64 v32, v34, -v34, s[0:1]
	ds_bpermute_b32 v34, v127, v6
	v_pk_mul_f32 v[8:9], v[8:9], v[160:161]
	v_pk_mul_f32 v[32:33], v[50:51], v[32:33]
	v_pk_mul_f32 v[22:23], v[36:37], v[0:1] op_sel_hi:[1,0]
	v_pk_fma_f32 v[4:5], v[58:59], v[4:5], v[32:33]
	s_waitcnt lgkmcnt(1)
; #define LAS __attribute__((address_space(3)))
; __device__ __forceinline__ u32x4 pack8(const float (&f)[8]) { u32x4 w; w.x = pk_bf16(f[0], f[1]); w.y = pk_bf16(f[2], f[3]); w.z = pk_bf16(f[4], f[5]); w.w = pk_bf16(f[6], f[7]); return w; }
; template <bool SAMPLE> ...
;     ...
;         for (int i = 0; i < 8; ++i) { const float pr = __shfl_xor(q[0][i], 32); q[0][i] = q[0][i] * cs[i] + sg * pr * sn[i]; }
;     }
;     bf16x8 qr[4];
; #pragma unroll
;     for (int d0 = 0; d0 < 4; ++d0) {
; #pragma unroll
;         for (int i = 0; i < 8; ++i) q[d0][i] *= 0.125f * LOG2E;
;         qr[d0] = __builtin_bit_cast(bf16x8, pack8(q[d0])); }
;     f32x16 p[5];
;     const int rq = SAMPLE ? (r32 & 7) : r32;
;     const int lo = rq + 1 - 4 * hi, hi_ = rq - 4 * hi;
;     float mx = -1e30f;
; #pragma unroll
;     for (int t = 0; t < 5; ++t) {
;         if (t >= tmin) {
; #pragma unroll
;             for (int i = 0; i < 16; ++i) p[t][i] = 0.f;
; #pragma unroll
;             for (int d0 = 0; d0 < 4; ++d0) { const bf16x8 kf = *(const LAS bf16x8*)(Kl + (32 * t + r32) * 144 + (16 * d0 + 8 * hi) * 2);
;                 p[t] = __builtin_amdgcn_mfma_f32_32x32x16_bf16(kf, qr[d0], p[t], 0, 0, 0); }
;             if (t == 0) {
; #pragma unroll
;                 for (int i = 0; i < 16; ++i) { const int kc = (i & 3) + 8 * (i >> 2); p[t][i] = (kc >= lo) ? p[t][i] : -1e30f; }
;             }
;             if (t == 4) {
; #pragma unroll
;                 for (int i = 0; i < 16; ++i) { const int kc = (i & 3) + 8 * (i >> 2); p[t][i] = (kc <= hi_) ? p[t][i] : -1e30f; }
	v_cndmask_b32_e64 v33, v35, -v35, s[0:1]
	ds_bpermute_b32 v35, v127, v9
	ds_bpermute_b32 v36, v127, v8
	s_waitcnt lgkmcnt(2)
	v_cndmask_b32_e64 v32, v34, -v34, s[0:1]
	v_pk_mul_f32 v[32:33], v[52:53], v[32:33]
	v_pk_mul_f32 v[10:11], v[24:25], v[0:1] op_sel_hi:[1,0]
	s_waitcnt vmcnt(0)
	v_pk_fma_f32 v[6:7], v[60:61], v[6:7], v[32:33]
	s_waitcnt lgkmcnt(1)
	v_cndmask_b32_e64 v33, v35, -v35, s[0:1]
	s_waitcnt lgkmcnt(0)
	v_cndmask_b32_e64 v32, v36, -v36, s[0:1]
	v_pk_mul_f32 v[12:13], v[26:27], v[0:1] op_sel_hi:[1,0]
	v_pk_mul_f32 v[14:15], v[28:29], v[0:1] op_sel_hi:[1,0]
	v_pk_mul_f32 v[32:33], v[54:55], v[32:33]
	v_pk_mul_f32 v[10:11], v[10:11], v[158:159]
	v_pk_mul_f32 v[12:13], v[12:13], v[154:155]
	v_pk_mul_f32 v[14:15], v[14:15], v[152:153]
	v_pk_mul_f32 v[16:17], v[30:31], v[0:1] op_sel_hi:[1,0]
	v_pk_fma_f32 v[8:9], v[62:63], v[8:9], v[32:33]
	v_pk_mul_f32 v[2:3], v[2:3], s[90:91] op_sel_hi:[1,0]
	v_pk_mul_f32 v[4:5], v[4:5], s[90:91] op_sel_hi:[1,0]
	v_pk_mul_f32 v[6:7], v[6:7], s[90:91] op_sel_hi:[1,0]
	v_pk_mul_f32 v[16:17], v[16:17], v[148:149]
	v_pk_mul_f32 v[18:19], v[18:19], v[146:147]
	v_pk_mul_f32 v[20:21], v[20:21], v[142:143]
	v_pk_mul_f32 v[22:23], v[22:23], v[140:141]
	v_pk_mul_f32 v[24:25], v[38:39], v[0:1] op_sel_hi:[1,0]
	v_pk_mul_f32 v[26:27], v[40:41], v[0:1] op_sel_hi:[1,0]
	v_pk_mul_f32 v[28:29], v[42:43], v[0:1] op_sel_hi:[1,0]
	v_pk_mul_f32 v[30:31], v[44:45], v[0:1] op_sel_hi:[1,0]
	v_pk_mul_f32 v[0:1], v[46:47], v[0:1] op_sel_hi:[1,0]
	v_pk_mul_f32 v[8:9], v[8:9], s[90:91] op_sel_hi:[1,0]
	v_cvt_pk_bf16_f32 v48, v2, v3
	v_cvt_pk_bf16_f32 v49, v4, v5
	v_cvt_pk_bf16_f32 v50, v6, v7
	v_pk_mul_f32 v[2:3], v[10:11], s[90:91] op_sel_hi:[1,0]
	v_pk_mul_f32 v[4:5], v[12:13], s[90:91] op_sel_hi:[1,0]
	v_pk_mul_f32 v[6:7], v[14:15], s[90:91] op_sel_hi:[1,0]
	v_pk_mul_f32 v[24:25], v[24:25], v[136:137]
	v_pk_mul_f32 v[26:27], v[26:27], v[122:123]
	v_pk_mul_f32 v[28:29], v[28:29], v[118:119]
	v_pk_mul_f32 v[30:31], v[30:31], v[116:117]
	v_pk_mul_f32 v[0:1], v[0:1], v[112:113]
	v_cvt_pk_bf16_f32 v51, v8, v9
	v_pk_mul_f32 v[8:9], v[16:17], s[90:91] op_sel_hi:[1,0]
	v_cvt_pk_bf16_f32 v112, v2, v3
	v_cvt_pk_bf16_f32 v113, v4, v5
	v_cvt_pk_bf16_f32 v114, v6, v7
	v_pk_mul_f32 v[2:3], v[18:19], s[90:91] op_sel_hi:[1,0]
	v_pk_mul_f32 v[4:5], v[20:21], s[90:91] op_sel_hi:[1,0]
	v_pk_mul_f32 v[6:7], v[22:23], s[90:91] op_sel_hi:[1,0]
	v_lshlrev_b32_e32 v136, 2, v125
	v_lshlrev_b32_e32 v149, 4, v125
	v_cvt_pk_bf16_f32 v115, v8, v9
	v_pk_mul_f32 v[8:9], v[24:25], s[90:91] op_sel_hi:[1,0]
	v_cvt_pk_bf16_f32 v116, v2, v3
	v_cvt_pk_bf16_f32 v117, v4, v5
	v_cvt_pk_bf16_f32 v118, v6, v7
	v_pk_mul_f32 v[2:3], v[26:27], s[90:91] op_sel_hi:[1,0]
	v_pk_mul_f32 v[4:5], v[28:29], s[90:91] op_sel_hi:[1,0]
	v_pk_mul_f32 v[6:7], v[30:31], s[90:91] op_sel_hi:[1,0]
	v_pk_mul_f32 v[0:1], v[0:1], s[90:91] op_sel_hi:[1,0]
	v_add_u32_e32 v32, s85, v149
	v_sub_u32_e32 v129, v134, v136
	v_cvt_pk_bf16_f32 v119, v8, v9
	v_cvt_pk_bf16_f32 v120, v2, v3
	v_cvt_pk_bf16_f32 v121, v4, v5
	v_cvt_pk_bf16_f32 v122, v6, v7
	v_cvt_pk_bf16_f32 v123, v0, v1
	v_mov_b32_e32 v0, 0xf149f2ca
	s_and_b64 vcc, exec, s[4:5]
	v_mad_u32_u24 v156, v134, s84, v32
	v_add_u32_e32 v147, 1, v129
	v_mov_b32_e32 v137, 0xf149f2ca
	v_mov_b32_e32 v140, 0xf149f2ca
	v_mov_b32_e32 v141, 0xf149f2ca
	v_mov_b32_e32 v142, 0xf149f2ca
	v_mov_b32_e32 v143, 0xf149f2ca
	v_mov_b32_e32 v145, 0xf149f2ca
	v_mov_b32_e32 v150, 0xf149f2ca
	v_mov_b32_e32 v151, 0xf149f2ca
	v_mov_b32_e32 v152, 0xf149f2ca
	v_mov_b32_e32 v153, 0xf149f2ca
	v_mov_b32_e32 v154, 0xf149f2ca
	v_mov_b32_e32 v155, 0xf149f2ca
	v_mov_b32_e32 v157, 0xf149f2ca
	s_cbranch_vccz .LBB0_477
	ds_read_b128 v[2:5], v156
	ds_read_b128 v[18:21], v156 offset:32
	v_cmp_gt_i32_e32 vcc, 1, v147
	s_waitcnt lgkmcnt(1)
	v_mfma_f32_32x32x16_bf16 v[2:17], v[2:5], v[48:51], 0
	s_waitcnt lgkmcnt(0)
	v_mfma_f32_32x32x16_bf16 v[2:17], v[18:21], v[112:115], v[2:17]
	ds_read_b128 v[18:21], v156 offset:64
	ds_read_b128 v[22:25], v156 offset:96
	s_waitcnt lgkmcnt(1)
	v_mfma_f32_32x32x16_bf16 v[2:17], v[18:21], v[116:119], v[2:17]
	s_waitcnt lgkmcnt(0)
	v_mfma_f32_32x32x16_bf16 v[2:17], v[22:25], v[120:123], v[2:17]
	s_nop 11
	v_cndmask_b32_e32 v137, v223, v2, vcc
	v_cmp_gt_i32_e32 vcc, 2, v147
	s_nop 1
	v_cndmask_b32_e32 v138, v223, v3, vcc
	v_cmp_gt_i32_e32 vcc, 3, v147
	s_nop 1
	v_cndmask_b32_e32 v139, v223, v4, vcc
	v_cmp_gt_i32_e32 vcc, 4, v147
	s_nop 1
	v_cndmask_b32_e32 v140, v223, v5, vcc
	v_cmp_gt_i32_e32 vcc, 9, v147
	s_nop 1
	v_cndmask_b32_e32 v141, v223, v6, vcc
	v_cmp_gt_i32_e32 vcc, 10, v147
	s_nop 1
	v_cndmask_b32_e32 v142, v223, v7, vcc
	v_cmp_gt_i32_e32 vcc, 11, v147
	s_nop 1
	v_cndmask_b32_e32 v143, v223, v8, vcc
	v_cmp_gt_i32_e32 vcc, 12, v147
	s_nop 1
	v_cndmask_b32_e32 v144, v223, v9, vcc
	v_cmp_gt_i32_e32 vcc, 17, v147
	s_nop 1
	v_cndmask_b32_e32 v145, v223, v10, vcc
	v_cmp_gt_i32_e32 vcc, 18, v147
	s_nop 1
	v_cndmask_b32_e32 v150, v223, v11, vcc
	v_cmp_gt_i32_e32 vcc, 19, v147
	s_nop 1
	v_cndmask_b32_e32 v151, v223, v12, vcc
	v_cmp_gt_i32_e32 vcc, 20, v147
	s_nop 1
	v_cndmask_b32_e32 v152, v223, v13, vcc
	v_cmp_gt_i32_e32 vcc, 25, v147
	s_nop 1
	v_cndmask_b32_e32 v153, v223, v14, vcc
	v_cmp_gt_i32_e32 vcc, 26, v147
	s_nop 1
	v_cndmask_b32_e32 v154, v223, v15, vcc
	v_cmp_gt_i32_e32 vcc, 27, v147
	s_nop 1
	v_cndmask_b32_e32 v155, v223, v16, vcc
	v_cmp_gt_i32_e32 vcc, 28, v147
	s_nop 1
	v_cndmask_b32_e32 v157, v223, v17, vcc

; #define PG8_STAGE(bufoff, gbase, voff) do { _Pragma("unroll") for (int _i = 0; _i < 2; ++_i) \
;         __builtin_amdgcn_global_load_lds((const unsigned*)((const char*)(gbase) + (voff)[_i]), (PG8_LAS unsigned*)(lds + (bufoff) + ldsw + _i * 8192), 16, 0, 0); } while (0)
; #define PG8_LDA(dst, b, h) do { _Pragma("unroll") for (int m = 0; m < 4; ++m) _Pragma("unroll") for (int k = 0; k < 2; ++k) dst[m][k] = *(const PG8_LAS bf16x8*)(lds + PG8_SA(b, h) + aoff + m * 2048 + k * 1024); } while (0)
; #define PG8_LDB(dst, b, h) do { _Pragma("unroll") for (int n = 0; n < 2; ++n) _Pragma("unroll") for (int k = 0; k < 2; ++k) dst[n][k] = *(const PG8_LAS bf16x8*)(lds + PG8_SB(b, h) + boff + n * 2048 + k * 1024); } while (0)
; #define PG8_MMA(ai, bj, At, Bt) do { __builtin_amdgcn_s_setprio(1); _Pragma("unroll") for (int m = 0; m < 4; ++m) _Pragma("unroll") for (int n = 0; n < 2; ++n) _Pragma("unroll") for (int k = 0; k < 2; ++k) \
;         acc[ai][bj][m][n] = __builtin_amdgcn_mfma_f32_16x16x32_bf16(Bt[n][k], At[m][k], acc[ai][bj][m][n], 0, 0, 0); __builtin_amdgcn_s_setprio(0); } while (0)
; #define PG8_WAIT_V(n) asm volatile("s_waitcnt vmcnt(" #n ")" ::: "memory")
; #define PG8_WAIT_L(n) asm volatile("s_waitcnt lgkmcnt(" #n ")" ::: "memory")
; #define PG8_BAR __builtin_amdgcn_s_barrier()
; #define PG8_SCHED __builtin_amdgcn_sched_barrier(0)
; template <class Epi, class Sched, bool ALIGN_EPI = false, bool SP2 = false>
; __device__ __forceinline__ void gemm_phase(PG8_LAS unsigned char* lds, const Gemm g, const Sched& S, const Epi& E) {
;     ...
;             PG8_LDB(B0, 0, 0); PG8_LDB(B1, 0, 1); PG8_SCHED; PG8_LDA(At, 0, 0); PG8_STAGE(PG8_SA(1, 1), a1 + hstep, voffA);
;             PG8_WAIT_V(8); PG8_WAIT_L(0); PG8_BAR; PG8_MMA(0, 0, At, B0); PG8_MMA(0, 1, At, B1); PG8_BAR; PG8_SCHED;
;             PG8_LDA(At, 0, 1); PG8_STAGE(PG8_SB(0, 0), b2, voffB); PG8_STAGE(PG8_SB(0, 1), b2 + hstep, voffB); PG8_STAGE(PG8_SA(0, 0), a2, voffA);
;             PG8_WAIT_V(8); PG8_WAIT_L(0); PG8_BAR; PG8_MMA(1, 0, At, B0); PG8_MMA(1, 1, At, B1); PG8_BAR; PG8_SCHED;
.LBB0_613:
	s_add_u32 s36, s34, 0xfffc0080
	s_addc_u32 s37, s35, -1
	s_add_i32 s68, 0, 0x10000
	s_cmp_eq_u32 s67, 12
	s_cselect_b32 s39, s27, s37
	s_cselect_b32 s38, s63, s36
	s_cselect_b32 s37, s25, s66
	s_cselect_b32 s36, s64, s65
	s_add_i32 s70, 0, 0x14000
	v_add_u32_e32 v84, s68, v228
	v_add_u32_e32 v156, s70, v228
	ds_read_b128 v[68:71], v84
	ds_read_b128 v[72:75], v84 offset:1024
	ds_read_b128 v[80:83], v84 offset:2048
	ds_read_b128 v[84:87], v84 offset:3072
	ds_read_b128 v[144:147], v156
	ds_read_b128 v[148:151], v156 offset:1024
	ds_read_b128 v[152:155], v156 offset:2048
	ds_read_b128 v[156:159], v156 offset:3072
	v_lshl_add_u64 v[210:211], s[34:35], 0, v[188:189]
	s_add_i32 m0, s52, 0xc000
	ds_read_b128 v[160:163], v230
	ds_read_b128 v[164:167], v230 offset:1024
	ds_read_b128 v[168:171], v230 offset:2048
	ds_read_b128 v[192:195], v230 offset:3072
	ds_read_b128 v[196:199], v230 offset:4096
	ds_read_b128 v[200:203], v230 offset:5120
	ds_read_b128 v[204:207], v230 offset:6144
	ds_read_b128 v[236:239], v230 offset:7168
	global_load_lds_dwordx4 v[210:211], off
	v_lshl_add_u64 v[210:211], s[34:35], 0, v[190:191]
	s_add_i32 m0, s52, 0xe000
	s_nop 0
	global_load_lds_dwordx4 v[210:211], off
	s_waitcnt vmcnt(8)
	s_waitcnt lgkmcnt(0)
	s_barrier
	s_setprio 1
	s_waitcnt lgkmcnt(0)
	v_mfma_f32_16x16x32_bf16 v[140:143], v[68:71], v[160:163], v[140:143]
	v_mfma_f32_16x16x32_bf16 v[136:139], v[80:83], v[160:163], v[136:139]
	v_mfma_f32_16x16x32_bf16 v[124:127], v[68:71], v[168:171], v[124:127]
	v_mfma_f32_16x16x32_bf16 v[120:123], v[80:83], v[168:171], v[120:123]
	v_mfma_f32_16x16x32_bf16 v[108:111], v[68:71], v[196:199], v[108:111]
	v_mfma_f32_16x16x32_bf16 v[104:107], v[80:83], v[196:199], v[104:107]
	v_mfma_f32_16x16x32_bf16 v[92:95], v[68:71], v[204:207], v[92:95]
	v_mfma_f32_16x16x32_bf16 v[88:91], v[80:83], v[204:207], v[88:91]
	v_mfma_f32_16x16x32_bf16 v[140:143], v[72:75], v[164:167], v[140:143]
	v_mfma_f32_16x16x32_bf16 v[136:139], v[84:87], v[164:167], v[136:139]
	v_mfma_f32_16x16x32_bf16 v[124:127], v[72:75], v[192:195], v[124:127]
	v_mfma_f32_16x16x32_bf16 v[120:123], v[84:87], v[192:195], v[120:123]
	v_mfma_f32_16x16x32_bf16 v[108:111], v[72:75], v[200:203], v[108:111]
	v_mfma_f32_16x16x32_bf16 v[104:107], v[84:87], v[200:203], v[104:107]
	v_mfma_f32_16x16x32_bf16 v[92:95], v[72:75], v[236:239], v[92:95]
	v_mfma_f32_16x16x32_bf16 v[88:91], v[84:87], v[236:239], v[88:91]
	s_setprio 0
	s_setprio 1
	v_mfma_f32_16x16x32_bf16 v[132:135], v[144:147], v[160:163], v[132:135]
	v_mfma_f32_16x16x32_bf16 v[128:131], v[152:155], v[160:163], v[128:131]
	v_mfma_f32_16x16x32_bf16 v[116:119], v[144:147], v[168:171], v[116:119]
	v_mfma_f32_16x16x32_bf16 v[112:115], v[152:155], v[168:171], v[112:115]
	v_mfma_f32_16x16x32_bf16 v[100:103], v[144:147], v[196:199], v[100:103]
	v_mfma_f32_16x16x32_bf16 v[96:99], v[152:155], v[196:199], v[96:99]
	v_mfma_f32_16x16x32_bf16 v[76:79], v[144:147], v[204:207], v[76:79]
	v_mfma_f32_16x16x32_bf16 v[64:67], v[152:155], v[204:207], v[64:67]
	v_mfma_f32_16x16x32_bf16 v[132:135], v[148:151], v[164:167], v[132:135]
	v_mfma_f32_16x16x32_bf16 v[128:131], v[156:159], v[164:167], v[128:131]
	v_mfma_f32_16x16x32_bf16 v[116:119], v[148:151], v[192:195], v[116:119]
	v_mfma_f32_16x16x32_bf16 v[112:115], v[156:159], v[192:195], v[112:115]
	s_setprio 2
	s_barrier
	v_mfma_f32_16x16x32_bf16 v[100:103], v[148:151], v[200:203], v[100:103]
	v_mfma_f32_16x16x32_bf16 v[96:99], v[156:159], v[200:203], v[96:99]
	v_mfma_f32_16x16x32_bf16 v[76:79], v[148:151], v[236:239], v[76:79]
	v_mfma_f32_16x16x32_bf16 v[64:67], v[156:159], v[236:239], v[64:67]
	s_setprio 0
	s_add_i32 s68, s68, s45
	v_lshl_add_u64 v[210:211], s[36:37], 0, v[172:173]
	s_mov_b32 m0, s68
	ds_read_b128 v[160:163], v230 offset:16384
	ds_read_b128 v[164:167], v230 offset:17408
	ds_read_b128 v[168:171], v230 offset:18432
	ds_read_b128 v[192:195], v230 offset:19456
	ds_read_b128 v[196:199], v230 offset:20480
	ds_read_b128 v[200:203], v230 offset:21504
	ds_read_b128 v[204:207], v230 offset:22528
	ds_read_b128 v[236:239], v230 offset:23552
	global_load_lds_dwordx4 v[210:211], off
	s_add_i32 m0, s68, 0x2000
	s_add_u32 s68, s36, 0x40000
	v_lshl_add_u64 v[240:241], s[36:37], 0, v[182:183]
	s_addc_u32 s69, s37, 0
	s_add_i32 s70, s70, s45
	global_load_lds_dwordx4 v[240:241], off
	v_lshl_add_u64 v[242:243], s[68:69], 0, v[172:173]
	s_mov_b32 m0, s70
	v_lshl_add_u64 v[244:245], s[38:39], 0, v[184:185]
	global_load_lds_dwordx4 v[242:243], off
	v_lshl_add_u64 v[242:243], s[68:69], 0, v[182:183]
	s_add_i32 m0, s70, 0x2000
	s_nop 0
	global_load_lds_dwordx4 v[242:243], off
	v_lshl_add_u64 v[242:243], s[38:39], 0, v[186:187]
	s_mov_b32 m0, s52
	s_nop 0
	global_load_lds_dwordx4 v[242:243], off
	s_mov_b32 m0, s53
	s_nop 0
	global_load_lds_dwordx4 v[244:245], off
	s_waitcnt vmcnt(8)
	s_waitcnt lgkmcnt(0)
	s_barrier
; #define PG8_STAGE(bufoff, gbase, voff) do { _Pragma("unroll") for (int _i = 0; _i < 2; ++_i) \
;         __builtin_amdgcn_global_load_lds((const unsigned*)((const char*)(gbase) + (voff)[_i]), (PG8_LAS unsigned*)(lds + (bufoff) + ldsw + _i * 8192), 16, 0, 0); } while (0)
; #define PG8_LDA(dst, b, h) do { _Pragma("unroll") for (int m = 0; m < 4; ++m) _Pragma("unroll") for (int k = 0; k < 2; ++k) dst[m][k] = *(const PG8_LAS bf16x8*)(lds + PG8_SA(b, h) + aoff + m * 2048 + k * 1024); } while (0)
; #define PG8_LDB(dst, b, h) do { _Pragma("unroll") for (int n = 0; n < 2; ++n) _Pragma("unroll") for (int k = 0; k < 2; ++k) dst[n][k] = *(const PG8_LAS bf16x8*)(lds + PG8_SB(b, h) + boff + n * 2048 + k * 1024); } while (0)
; #define PG8_MMA(ai, bj, At, Bt) do { __builtin_amdgcn_s_setprio(1); _Pragma("unroll") for (int m = 0; m < 4; ++m) _Pragma("unroll") for (int n = 0; n < 2; ++n) _Pragma("unroll") for (int k = 0; k < 2; ++k) \
;         acc[ai][bj][m][n] = __builtin_amdgcn_mfma_f32_16x16x32_bf16(Bt[n][k], At[m][k], acc[ai][bj][m][n], 0, 0, 0); __builtin_amdgcn_s_setprio(0); } while (0)
; #define PG8_WAIT_V(n) asm volatile("s_waitcnt vmcnt(" #n ")" ::: "memory")
; #define PG8_WAIT_L(n) asm volatile("s_waitcnt lgkmcnt(" #n ")" ::: "memory")
; #define PG8_BAR __builtin_amdgcn_s_barrier()
; #define PG8_SCHED __builtin_amdgcn_sched_barrier(0)
; template <class Epi, class Sched, bool ALIGN_EPI = false, bool SP2 = false>
; __device__ __forceinline__ void gemm_phase(PG8_LAS unsigned char* lds, const Gemm g, const Sched& S, const Epi& E) {
;     ...
;             PG8_WAIT_V(8); PG8_WAIT_L(0); PG8_BAR; PG8_MMA(1, 0, At, B0); PG8_MMA(1, 1, At, B1); PG8_BAR; PG8_SCHED;
;             PG8_LDB(B0, 1, 0); PG8_LDB(B1, 1, 1); PG8_SCHED; PG8_LDA(At, 1, 0); PG8_STAGE(PG8_SA(0, 1), a2 + hstep, voffA);
;             PG8_WAIT_V(8); PG8_WAIT_L(0); PG8_BAR; PG8_MMA(0, 0, At, B0); PG8_MMA(0, 1, At, B1); PG8_BAR; PG8_SCHED;
	s_setprio 1
	s_waitcnt lgkmcnt(0)
	v_mfma_f32_16x16x32_bf16 v[60:63], v[68:71], v[160:163], v[60:63]
	v_mfma_f32_16x16x32_bf16 v[56:59], v[80:83], v[160:163], v[56:59]
	v_mfma_f32_16x16x32_bf16 v[44:47], v[68:71], v[168:171], v[44:47]
	v_mfma_f32_16x16x32_bf16 v[40:43], v[80:83], v[168:171], v[40:43]
	v_mfma_f32_16x16x32_bf16 v[28:31], v[68:71], v[196:199], v[28:31]
	v_mfma_f32_16x16x32_bf16 v[24:27], v[80:83], v[196:199], v[24:27]
	v_mfma_f32_16x16x32_bf16 v[12:15], v[68:71], v[204:207], v[12:15]
	v_mfma_f32_16x16x32_bf16 v[8:11], v[80:83], v[204:207], v[8:11]
	v_mfma_f32_16x16x32_bf16 v[60:63], v[72:75], v[164:167], v[60:63]
	v_mfma_f32_16x16x32_bf16 v[56:59], v[84:87], v[164:167], v[56:59]
	v_mfma_f32_16x16x32_bf16 v[44:47], v[72:75], v[192:195], v[44:47]
	v_mfma_f32_16x16x32_bf16 v[40:43], v[84:87], v[192:195], v[40:43]
	v_mfma_f32_16x16x32_bf16 v[28:31], v[72:75], v[200:203], v[28:31]
	v_mfma_f32_16x16x32_bf16 v[24:27], v[84:87], v[200:203], v[24:27]
	v_mfma_f32_16x16x32_bf16 v[12:15], v[72:75], v[236:239], v[12:15]
	v_mfma_f32_16x16x32_bf16 v[8:11], v[84:87], v[236:239], v[8:11]
	s_setprio 0
	s_setprio 1
	v_mfma_f32_16x16x32_bf16 v[52:55], v[144:147], v[160:163], v[52:55]
	v_mfma_f32_16x16x32_bf16 v[48:51], v[152:155], v[160:163], v[48:51]
	v_mfma_f32_16x16x32_bf16 v[36:39], v[144:147], v[168:171], v[36:39]
	v_mfma_f32_16x16x32_bf16 v[32:35], v[152:155], v[168:171], v[32:35]
	v_mfma_f32_16x16x32_bf16 v[20:23], v[144:147], v[196:199], v[20:23]
	v_mfma_f32_16x16x32_bf16 v[16:19], v[152:155], v[196:199], v[16:19]
	v_mfma_f32_16x16x32_bf16 v[4:7], v[144:147], v[204:207], v[4:7]
	v_mfma_f32_16x16x32_bf16 v[0:3], v[152:155], v[204:207], v[0:3]
	v_mfma_f32_16x16x32_bf16 v[52:55], v[148:151], v[164:167], v[52:55]
	v_mfma_f32_16x16x32_bf16 v[48:51], v[156:159], v[164:167], v[48:51]
	v_mfma_f32_16x16x32_bf16 v[36:39], v[148:151], v[192:195], v[36:39]
	v_mfma_f32_16x16x32_bf16 v[32:35], v[156:159], v[192:195], v[32:35]
	s_setprio 2
	s_barrier
	v_mfma_f32_16x16x32_bf16 v[20:23], v[148:151], v[200:203], v[20:23]
	v_mfma_f32_16x16x32_bf16 v[16:19], v[156:159], v[200:203], v[16:19]
	v_mfma_f32_16x16x32_bf16 v[4:7], v[148:151], v[236:239], v[4:7]
	v_mfma_f32_16x16x32_bf16 v[0:3], v[156:159], v[236:239], v[0:3]
	s_setprio 0
	s_add_i32 s68, 0, 0x18000
	s_add_i32 s69, 0, 0x1c000
	v_add_u32_e32 v84, s68, v228
	v_add_u32_e32 v156, s69, v228
	ds_read_b128 v[68:71], v84
	ds_read_b128 v[72:75], v84 offset:1024
	ds_read_b128 v[80:83], v84 offset:2048
	ds_read_b128 v[84:87], v84 offset:3072
	ds_read_b128 v[144:147], v156
	ds_read_b128 v[148:151], v156 offset:1024
	ds_read_b128 v[152:155], v156 offset:2048
	ds_read_b128 v[156:159], v156 offset:3072
	s_add_u32 s38, s38, 0x40000
	s_addc_u32 s39, s39, 0
	s_mov_b32 m0, s54
	v_lshl_add_u64 v[246:247], s[38:39], 0, v[186:187]
	ds_read_b128 v[160:163], v230 offset:32768
	ds_read_b128 v[164:167], v230 offset:33792
	ds_read_b128 v[168:171], v230 offset:34816
	ds_read_b128 v[192:195], v230 offset:35840
	ds_read_b128 v[196:199], v230 offset:36864
	ds_read_b128 v[200:203], v230 offset:37888
	ds_read_b128 v[204:207], v230 offset:38912
	ds_read_b128 v[236:239], v230 offset:39936
	global_load_lds_dwordx4 v[246:247], off
	v_lshl_add_u64 v[246:247], s[38:39], 0, v[184:185]
	s_mov_b32 m0, s55
	s_nop 0
	global_load_lds_dwordx4 v[246:247], off
	s_waitcnt vmcnt(8)
	s_waitcnt lgkmcnt(0)
	s_barrier
	s_setprio 1
	s_waitcnt lgkmcnt(0)
	v_mfma_f32_16x16x32_bf16 v[140:143], v[68:71], v[160:163], v[140:143]
	v_mfma_f32_16x16x32_bf16 v[136:139], v[80:83], v[160:163], v[136:139]
	v_mfma_f32_16x16x32_bf16 v[124:127], v[68:71], v[168:171], v[124:127]
	v_mfma_f32_16x16x32_bf16 v[120:123], v[80:83], v[168:171], v[120:123]
	v_mfma_f32_16x16x32_bf16 v[108:111], v[68:71], v[196:199], v[108:111]
	v_mfma_f32_16x16x32_bf16 v[104:107], v[80:83], v[196:199], v[104:107]
	v_mfma_f32_16x16x32_bf16 v[92:95], v[68:71], v[204:207], v[92:95]
	v_mfma_f32_16x16x32_bf16 v[88:91], v[80:83], v[204:207], v[88:91]
	v_mfma_f32_16x16x32_bf16 v[140:143], v[72:75], v[164:167], v[140:143]
	v_mfma_f32_16x16x32_bf16 v[136:139], v[84:87], v[164:167], v[136:139]
	v_mfma_f32_16x16x32_bf16 v[124:127], v[72:75], v[192:195], v[124:127]
	v_mfma_f32_16x16x32_bf16 v[120:123], v[84:87], v[192:195], v[120:123]
	v_mfma_f32_16x16x32_bf16 v[108:111], v[72:75], v[200:203], v[108:111]
	v_mfma_f32_16x16x32_bf16 v[104:107], v[84:87], v[200:203], v[104:107]
	v_mfma_f32_16x16x32_bf16 v[92:95], v[72:75], v[236:239], v[92:95]
	v_mfma_f32_16x16x32_bf16 v[88:91], v[84:87], v[236:239], v[88:91]
	s_setprio 0
	s_setprio 1
	v_mfma_f32_16x16x32_bf16 v[132:135], v[144:147], v[160:163], v[132:135]
	v_mfma_f32_16x16x32_bf16 v[128:131], v[152:155], v[160:163], v[128:131]
	v_mfma_f32_16x16x32_bf16 v[116:119], v[144:147], v[168:171], v[116:119]
	v_mfma_f32_16x16x32_bf16 v[112:115], v[152:155], v[168:171], v[112:115]
	v_mfma_f32_16x16x32_bf16 v[100:103], v[144:147], v[196:199], v[100:103]
	v_mfma_f32_16x16x32_bf16 v[96:99], v[152:155], v[196:199], v[96:99]
	v_mfma_f32_16x16x32_bf16 v[76:79], v[144:147], v[204:207], v[76:79]
	v_mfma_f32_16x16x32_bf16 v[64:67], v[152:155], v[204:207], v[64:67]
	v_mfma_f32_16x16x32_bf16 v[132:135], v[148:151], v[164:167], v[132:135]
	v_mfma_f32_16x16x32_bf16 v[128:131], v[156:159], v[164:167], v[128:131]
	v_mfma_f32_16x16x32_bf16 v[116:119], v[148:151], v[192:195], v[116:119]
	v_mfma_f32_16x16x32_bf16 v[112:115], v[156:159], v[192:195], v[112:115]
	s_setprio 2
	s_barrier
; #define PG8_STAGE(bufoff, gbase, voff) do { _Pragma("unroll") for (int _i = 0; _i < 2; ++_i) \
;         __builtin_amdgcn_global_load_lds((const unsigned*)((const char*)(gbase) + (voff)[_i]), (PG8_LAS unsigned*)(lds + (bufoff) + ldsw + _i * 8192), 16, 0, 0); } while (0)
; #define PG8_LDA(dst, b, h) do { _Pragma("unroll") for (int m = 0; m < 4; ++m) _Pragma("unroll") for (int k = 0; k < 2; ++k) dst[m][k] = *(const PG8_LAS bf16x8*)(lds + PG8_SA(b, h) + aoff + m * 2048 + k * 1024); } while (0)
; #define PG8_MMA(ai, bj, At, Bt) do { __builtin_amdgcn_s_setprio(1); _Pragma("unroll") for (int m = 0; m < 4; ++m) _Pragma("unroll") for (int n = 0; n < 2; ++n) _Pragma("unroll") for (int k = 0; k < 2; ++k) \
;         acc[ai][bj][m][n] = __builtin_amdgcn_mfma_f32_16x16x32_bf16(Bt[n][k], At[m][k], acc[ai][bj][m][n], 0, 0, 0); __builtin_amdgcn_s_setprio(0); } while (0)
; #define PG8_WAIT_V(n) asm volatile("s_waitcnt vmcnt(" #n ")" ::: "memory")
; #define PG8_WAIT_L(n) asm volatile("s_waitcnt lgkmcnt(" #n ")" ::: "memory")
; #define PG8_BAR __builtin_amdgcn_s_barrier()
; #define PG8_SCHED __builtin_amdgcn_sched_barrier(0)
; template <class Epi, class Sched, bool ALIGN_EPI = false, bool SP2 = false>
; __device__ __forceinline__ void gemm_phase(PG8_LAS unsigned char* lds, const Gemm g, const Sched& S, const Epi& E) {
;     ...
;         for (int t = 0; t < nt; t += 2) {
;     ...
;             PG8_WAIT_V(8); PG8_WAIT_L(0); PG8_BAR; PG8_MMA(0, 0, At, B0); PG8_MMA(0, 1, At, B1); PG8_BAR; PG8_SCHED;
;             PG8_LDA(At, 1, 1); PG8_STAGE(PG8_SB(1, 0), b3, voffB); PG8_STAGE(PG8_SB(1, 1), b3 + hstep, voffB); PG8_STAGE(PG8_SA(1, 0), a3, voffA);
;             PG8_WAIT_V(8); PG8_WAIT_L(0); PG8_BAR; PG8_MMA(1, 0, At, B0); PG8_MMA(1, 1, At, B1); PG8_BAR; PG8_SCHED;
	v_mfma_f32_16x16x32_bf16 v[100:103], v[148:151], v[200:203], v[100:103]
	v_mfma_f32_16x16x32_bf16 v[96:99], v[156:159], v[200:203], v[96:99]
	v_mfma_f32_16x16x32_bf16 v[76:79], v[148:151], v[236:239], v[76:79]
	v_mfma_f32_16x16x32_bf16 v[64:67], v[156:159], v[236:239], v[64:67]
	s_setprio 0
	s_add_i32 s38, s68, s45
	v_lshl_add_u64 v[210:211], v[210:211], 0, s[88:89]
	s_mov_b32 m0, s38
	ds_read_b128 v[160:163], v230 offset:49152
	ds_read_b128 v[164:167], v230 offset:50176
	ds_read_b128 v[168:171], v230 offset:51200
	ds_read_b128 v[192:195], v230 offset:52224
	ds_read_b128 v[196:199], v230 offset:53248
	ds_read_b128 v[200:203], v230 offset:54272
	ds_read_b128 v[204:207], v230 offset:55296
	ds_read_b128 v[236:239], v230 offset:56320
	global_load_lds_dwordx4 v[210:211], off
	s_add_i32 m0, s38, 0x2000
	s_add_u32 s36, s36, 0x40080
	v_lshl_add_u64 v[210:211], v[240:241], 0, s[88:89]
	s_addc_u32 s37, s37, 0
	s_add_i32 s38, s69, s45
	global_load_lds_dwordx4 v[210:211], off
	v_lshl_add_u64 v[210:211], s[36:37], 0, v[172:173]
	s_mov_b32 m0, s38
	s_nop 0
	global_load_lds_dwordx4 v[210:211], off
	v_lshl_add_u64 v[210:211], s[36:37], 0, v[182:183]
	s_add_i32 m0, s38, 0x2000
	s_nop 0
	global_load_lds_dwordx4 v[210:211], off
	v_lshl_add_u64 v[210:211], v[242:243], 0, s[88:89]
	s_mov_b32 m0, s56
	s_nop 0
	global_load_lds_dwordx4 v[210:211], off
	v_lshl_add_u64 v[210:211], v[244:245], 0, s[88:89]
	s_mov_b32 m0, s57
	s_nop 0
	global_load_lds_dwordx4 v[210:211], off
	s_waitcnt vmcnt(8)
	s_waitcnt lgkmcnt(0)
	s_barrier
	s_setprio 1
	s_waitcnt lgkmcnt(0)
	v_mfma_f32_16x16x32_bf16 v[60:63], v[68:71], v[160:163], v[60:63]
	v_mfma_f32_16x16x32_bf16 v[56:59], v[80:83], v[160:163], v[56:59]
	v_mfma_f32_16x16x32_bf16 v[44:47], v[68:71], v[168:171], v[44:47]
	v_mfma_f32_16x16x32_bf16 v[40:43], v[80:83], v[168:171], v[40:43]
	v_mfma_f32_16x16x32_bf16 v[28:31], v[68:71], v[196:199], v[28:31]
	v_mfma_f32_16x16x32_bf16 v[24:27], v[80:83], v[196:199], v[24:27]
	v_mfma_f32_16x16x32_bf16 v[12:15], v[68:71], v[204:207], v[12:15]
	v_mfma_f32_16x16x32_bf16 v[8:11], v[80:83], v[204:207], v[8:11]
	v_mfma_f32_16x16x32_bf16 v[60:63], v[72:75], v[164:167], v[60:63]
	v_mfma_f32_16x16x32_bf16 v[56:59], v[84:87], v[164:167], v[56:59]
	v_mfma_f32_16x16x32_bf16 v[44:47], v[72:75], v[192:195], v[44:47]
	v_mfma_f32_16x16x32_bf16 v[40:43], v[84:87], v[192:195], v[40:43]
	v_mfma_f32_16x16x32_bf16 v[28:31], v[72:75], v[200:203], v[28:31]
	v_mfma_f32_16x16x32_bf16 v[24:27], v[84:87], v[200:203], v[24:27]
	v_mfma_f32_16x16x32_bf16 v[12:15], v[72:75], v[236:239], v[12:15]
	v_mfma_f32_16x16x32_bf16 v[8:11], v[84:87], v[236:239], v[8:11]
	s_setprio 0
	s_setprio 1
	v_mfma_f32_16x16x32_bf16 v[52:55], v[144:147], v[160:163], v[52:55]
	v_mfma_f32_16x16x32_bf16 v[48:51], v[152:155], v[160:163], v[48:51]
	v_mfma_f32_16x16x32_bf16 v[36:39], v[144:147], v[168:171], v[36:39]
	v_mfma_f32_16x16x32_bf16 v[32:35], v[152:155], v[168:171], v[32:35]
	v_mfma_f32_16x16x32_bf16 v[20:23], v[144:147], v[196:199], v[20:23]
	v_mfma_f32_16x16x32_bf16 v[16:19], v[152:155], v[196:199], v[16:19]
	v_mfma_f32_16x16x32_bf16 v[4:7], v[144:147], v[204:207], v[4:7]
	v_mfma_f32_16x16x32_bf16 v[0:3], v[152:155], v[204:207], v[0:3]
	v_mfma_f32_16x16x32_bf16 v[52:55], v[148:151], v[164:167], v[52:55]
	v_mfma_f32_16x16x32_bf16 v[48:51], v[156:159], v[164:167], v[48:51]
	v_mfma_f32_16x16x32_bf16 v[36:39], v[148:151], v[192:195], v[36:39]
	v_mfma_f32_16x16x32_bf16 v[32:35], v[156:159], v[192:195], v[32:35]
	s_setprio 2
	s_barrier
	v_mfma_f32_16x16x32_bf16 v[20:23], v[148:151], v[200:203], v[20:23]
	v_mfma_f32_16x16x32_bf16 v[16:19], v[156:159], v[200:203], v[16:19]
	v_mfma_f32_16x16x32_bf16 v[4:7], v[148:151], v[236:239], v[4:7]
	v_mfma_f32_16x16x32_bf16 v[0:3], v[156:159], v[236:239], v[0:3]
	s_setprio 0
	s_add_i32 s67, s67, 2
	s_add_u32 s34, s34, 0x100
	s_addc_u32 s35, s35, 0
	s_add_u32 s65, s65, 0x100
	s_addc_u32 s66, s66, 0
	s_cmp_gt_u32 s67, 13
	s_cbranch_scc0 .LBB0_613
	s_and_b64 vcc, exec, s[22:23]
	s_cbranch_vccz .LBB0_616
	s_barrier
